# compressed branch P*V: the four V-fragment LDS reads of each block issued together with counted waits
# baseline (speedup 1.0000x reference)
; #define LAS __attribute__((address_space(3)))
; DEV void attn_item(LAS unsigned char* lds, const bf16_t* P, const bf16_t* QB, const bf16_t* KV, const bf16_t* KC, const bf16_t* VC, const float* rel_bias, bf16_t* OB, int b, int g, int qt) {
;     ...
;                     for (int r = 0; r < 4; ++r) { const int n = kt * 16 + g4 * 4 + r; const int dist = tl - (16 * n + 31);
;                         const int idx = dist < 0 ? 0 : (dist > 128 ? 128 : dist);
;                         const float s = a[r] + *(const LAS float*)(lds + btb + idx * 4 + hh * 516);
;                         a[r] = dist >= 0 ? s : NEG_; }
;                     sc[kt] = a;
;                 } else sc[kt] = (f32x4){NEG_, NEG_, NEG_, NEG_};
;             }
;             float mx = NEG_;
; #pragma unroll
;             for (int kt = 0; kt < 8; ++kt)
; #pragma unroll
;                 for (int r = 0; r < 4; ++r) mx = fmaxf(mx, sc[kt][r]);
;             mx = fmaxf(mx, __shfl_xor(mx, 16)); mx = fmaxf(mx, __shfl_xor(mx, 32));
;             float rs = 0.f;
; #pragma unroll
;             for (int kt = 0; kt < 8; ++kt)
; #pragma unroll
;                 for (int r = 0; r < 4; ++r) { const float s = sc[kt][r]; const float p = s > -1e29f ? __builtin_amdgcn_exp2f(s - mx) : 0.f; sc[kt][r] = p; rs += p; }
;             rs += __shfl_xor(rs, 16); rs += __shfl_xor(rs, 32);
.LBB0_185:
	s_waitcnt lgkmcnt(3)
	v_add_f32_e32 v2, v2, v35
	v_cmp_lt_i32_e64 s[42:43], -1, v33
	s_waitcnt lgkmcnt(2)
	v_add_f32_e32 v3, v3, v37
	v_cmp_lt_i32_e64 s[44:45], -1, v36
	v_cndmask_b32_e64 v2, v223, v2, s[42:43]
	s_waitcnt lgkmcnt(1)
	v_add_f32_e32 v4, v4, v39
	v_cndmask_b32_e64 v3, v223, v3, s[44:45]
	v_cmp_lt_i32_e64 s[46:47], -1, v38
	s_waitcnt lgkmcnt(0)
	v_add_f32_e32 v5, v5, v41
	v_cmp_lt_i32_e64 s[48:49], -1, v40
	s_mov_b32 s25, 0xf149f2ca
	v_cndmask_b32_e64 v4, v223, v4, s[46:47]
	v_cndmask_b32_e64 v5, v223, v5, s[48:49]
	v_max3_f32 v33, v2, s25, v3
	v_max3_f32 v33, v33, v4, v5
	v_max3_f32 v33, v33, v45, v44
	v_max3_f32 v33, v33, v43, v42
	v_max3_f32 v33, v33, v34, v49
	v_max3_f32 v33, v33, v47, v46
	v_max3_f32 v33, v33, v54, v53
	v_max3_f32 v33, v33, v52, v51
	v_max3_f32 v33, v33, v50, v57
	v_max3_f32 v33, v33, v56, v55
	v_max3_f32 v33, v33, v62, v61
	v_and_b32_e32 v70, 64, v213
	v_max3_f32 v33, v33, v60, v59
	v_xor_b32_e32 v48, 16, v213
	v_add_u32_e32 v153, 64, v70
	v_max3_f32 v33, v33, v58, v65
	v_cmp_lt_i32_e32 vcc, v48, v153
	v_max3_f32 v33, v33, v64, v63
	v_max3_f32 v33, v33, v66, v69
	v_cndmask_b32_e32 v48, v213, v48, vcc
	v_lshlrev_b32_e32 v143, 2, v48
	v_max3_f32 v33, v33, v68, v67
	ds_bpermute_b32 v35, v143, v33
	v_xor_b32_e32 v36, 32, v213
	v_cmp_lt_i32_e32 vcc, v36, v153
	v_add_u32_e32 v154, 0, v32
	v_add_u32_e32 v155, 0x1000, v154
	v_cndmask_b32_e32 v36, v213, v36, vcc
	s_waitcnt lgkmcnt(0)
	v_max_f32_e32 v35, v35, v35
	v_lshlrev_b32_e32 v144, 2, v36
	v_max_f32_e32 v33, v33, v35
	ds_bpermute_b32 v35, v144, v33
	v_cmp_lt_f32_e32 vcc, s65, v2
	v_add_u32_e32 v156, 0x2000, v154
	v_add_u32_e32 v157, 0x3000, v154
	s_waitcnt lgkmcnt(0)
	v_max_f32_e32 v35, v35, v35
	v_max_f32_e32 v33, v33, v35
	v_sub_f32_e32 v35, v2, v33
	v_exp_f32_e32 v35, v35
	v_sub_f32_e32 v36, v3, v33
	v_exp_f32_e32 v36, v36
	v_sub_f32_e32 v37, v5, v33
	v_cndmask_b32_e32 v2, 0, v35, vcc
	v_cmp_lt_f32_e32 vcc, s65, v3
	v_exp_f32_e32 v37, v37
	v_add_f32_e32 v35, 0, v2
	v_cndmask_b32_e32 v3, 0, v36, vcc
	v_sub_f32_e32 v36, v4, v33
	v_exp_f32_e32 v36, v36
	v_cmp_lt_f32_e32 vcc, s65, v4
	v_add_f32_e32 v35, v3, v35
	s_nop 0
	v_cndmask_b32_e32 v4, 0, v36, vcc
	v_sub_f32_e32 v36, v45, v33
	v_exp_f32_e32 v36, v36
	v_cmp_lt_f32_e32 vcc, s65, v5
	v_add_f32_e32 v35, v4, v35
	s_nop 0
	v_cndmask_b32_e32 v5, 0, v37, vcc
	v_sub_f32_e32 v37, v44, v33
	v_cmp_lt_f32_e32 vcc, s65, v45
	v_exp_f32_e32 v37, v37
	v_add_f32_e32 v35, v5, v35
	v_cndmask_b32_e32 v38, 0, v36, vcc
	v_sub_f32_e32 v36, v43, v33
	v_exp_f32_e32 v36, v36
	v_cmp_lt_f32_e32 vcc, s65, v44
	v_add_f32_e32 v35, v38, v35
	s_nop 0
	v_cndmask_b32_e32 v39, 0, v37, vcc
	v_sub_f32_e32 v37, v42, v33
	v_cmp_lt_f32_e32 vcc, s65, v43
	v_exp_f32_e32 v37, v37
	v_add_f32_e32 v35, v39, v35
	v_cndmask_b32_e32 v40, 0, v36, vcc
	v_sub_f32_e32 v36, v34, v33
	v_exp_f32_e32 v36, v36
	v_cmp_lt_f32_e32 vcc, s65, v42
	v_add_f32_e32 v35, v40, v35
	v_sub_f32_e32 v42, v46, v33
	v_cndmask_b32_e32 v41, 0, v37, vcc
	v_cmp_lt_f32_e32 vcc, s65, v34
	v_add_f32_e32 v35, v41, v35
	v_sub_f32_e32 v37, v49, v33
	v_cndmask_b32_e32 v36, 0, v36, vcc
	v_exp_f32_e32 v37, v37
	v_add_f32_e32 v34, v36, v35
	v_sub_f32_e32 v35, v47, v33
	v_exp_f32_e32 v35, v35
	v_cmp_lt_f32_e32 vcc, s65, v49
	v_exp_f32_e32 v42, v42
	s_nop 0
	v_cndmask_b32_e32 v37, 0, v37, vcc
	v_cmp_lt_f32_e32 vcc, s65, v47
	v_add_f32_e32 v34, v37, v34
	s_nop 0
	v_cndmask_b32_e32 v70, 0, v35, vcc
	v_sub_f32_e32 v35, v54, v33
	v_exp_f32_e32 v35, v35
	v_cmp_lt_f32_e32 vcc, s65, v46
	v_add_f32_e32 v34, v70, v34
	s_nop 0
	v_cndmask_b32_e32 v71, 0, v42, vcc
	v_sub_f32_e32 v42, v53, v33
	v_cmp_lt_f32_e32 vcc, s65, v54
	v_exp_f32_e32 v42, v42
	v_add_f32_e32 v34, v71, v34
	v_cndmask_b32_e32 v72, 0, v35, vcc
	v_sub_f32_e32 v35, v52, v33
	v_exp_f32_e32 v35, v35
	v_cmp_lt_f32_e32 vcc, s65, v53
	v_add_f32_e32 v34, v72, v34
	s_nop 0
	v_cndmask_b32_e32 v73, 0, v42, vcc
	v_sub_f32_e32 v42, v51, v33
	v_cmp_lt_f32_e32 vcc, s65, v52
	v_exp_f32_e32 v42, v42
	v_add_f32_e32 v34, v73, v34
	v_cndmask_b32_e32 v76, 0, v35, vcc
	v_sub_f32_e32 v35, v50, v33
	v_exp_f32_e32 v35, v35
	v_cmp_lt_f32_e32 vcc, s65, v51
	v_add_f32_e32 v34, v76, v34
	s_nop 0
	v_cndmask_b32_e32 v77, 0, v42, vcc
	v_sub_f32_e32 v42, v57, v33
	v_cmp_lt_f32_e32 vcc, s65, v50
	v_exp_f32_e32 v42, v42
	v_add_f32_e32 v34, v77, v34
	v_cndmask_b32_e32 v50, 0, v35, vcc
	v_sub_f32_e32 v35, v56, v33
	v_exp_f32_e32 v35, v35
	v_cmp_lt_f32_e32 vcc, s65, v57
	v_add_f32_e32 v34, v50, v34
	s_nop 0
	v_cndmask_b32_e32 v51, 0, v42, vcc
	v_sub_f32_e32 v42, v55, v33
	v_cmp_lt_f32_e32 vcc, s65, v56
	v_exp_f32_e32 v42, v42
	v_add_f32_e32 v34, v51, v34
	v_cndmask_b32_e32 v54, 0, v35, vcc
	v_sub_f32_e32 v35, v62, v33
	v_exp_f32_e32 v35, v35
	v_cmp_lt_f32_e32 vcc, s65, v55
	v_add_f32_e32 v34, v54, v34
	s_nop 0
	v_cndmask_b32_e32 v55, 0, v42, vcc
	v_sub_f32_e32 v42, v61, v33
	v_cmp_lt_f32_e32 vcc, s65, v62
	v_exp_f32_e32 v42, v42
	v_add_f32_e32 v34, v55, v34
	v_cndmask_b32_e32 v56, 0, v35, vcc
	v_sub_f32_e32 v35, v60, v33
	v_exp_f32_e32 v35, v35
	v_cmp_lt_f32_e32 vcc, s65, v61
	v_add_f32_e32 v34, v56, v34
	s_nop 0
	v_cndmask_b32_e32 v57, 0, v42, vcc
	v_sub_f32_e32 v42, v59, v33
	v_cmp_lt_f32_e32 vcc, s65, v60
	v_exp_f32_e32 v42, v42
	v_add_f32_e32 v34, v57, v34
	v_cndmask_b32_e32 v78, 0, v35, vcc
	v_sub_f32_e32 v35, v58, v33
	v_exp_f32_e32 v35, v35
	v_cmp_lt_f32_e32 vcc, s65, v59
	v_add_f32_e32 v34, v78, v34
	s_nop 0
	v_cndmask_b32_e32 v79, 0, v42, vcc
	v_sub_f32_e32 v42, v65, v33
	v_cmp_lt_f32_e32 vcc, s65, v58
	v_exp_f32_e32 v42, v42
	v_add_f32_e32 v34, v79, v34
	v_cndmask_b32_e32 v44, 0, v35, vcc
	v_sub_f32_e32 v35, v64, v33
	v_exp_f32_e32 v35, v35
	v_cmp_lt_f32_e32 vcc, s65, v65
	v_add_f32_e32 v34, v44, v34
	s_nop 0
	v_cndmask_b32_e32 v45, 0, v42, vcc
	v_sub_f32_e32 v42, v63, v33
	v_cmp_lt_f32_e32 vcc, s65, v64
	v_exp_f32_e32 v42, v42
	v_add_f32_e32 v34, v45, v34
	v_cndmask_b32_e32 v46, 0, v35, vcc
	v_sub_f32_e32 v35, v66, v33
	v_exp_f32_e32 v35, v35
	v_cmp_lt_f32_e32 vcc, s65, v63
	v_add_f32_e32 v34, v46, v34
	s_nop 0
	v_cndmask_b32_e32 v47, 0, v42, vcc
	v_sub_f32_e32 v42, v69, v33
	v_cmp_lt_f32_e32 vcc, s65, v66
	v_exp_f32_e32 v42, v42
	v_add_f32_e32 v34, v47, v34
	v_cndmask_b32_e32 v48, 0, v35, vcc
	v_sub_f32_e32 v35, v68, v33
	v_exp_f32_e32 v35, v35
	v_sub_f32_e32 v33, v67, v33
	v_exp_f32_e32 v33, v33
	v_cmp_lt_f32_e32 vcc, s65, v69
	v_add_f32_e32 v34, v48, v34
	s_nop 0
	v_cndmask_b32_e32 v49, 0, v42, vcc
	v_cmp_lt_f32_e32 vcc, s65, v68
	v_add_f32_e32 v34, v49, v34
	s_nop 0
	v_cndmask_b32_e32 v52, 0, v35, vcc
	v_cmp_lt_f32_e32 vcc, s65, v67
	v_add_f32_e32 v34, v52, v34
	s_nop 0
	v_cndmask_b32_e32 v53, 0, v33, vcc
	v_add_f32_e32 v33, v53, v34
	ds_bpermute_b32 v34, v143, v33
	s_waitcnt lgkmcnt(0)
; #define LAS __attribute__((address_space(3)))
; DEV unsigned cvt_pk_bf16(float lo, float hi) { unsigned r; asm volatile("v_cvt_pk_bf16_f32 %0, %1, %2" : "=v"(r) : "v"(lo), "v"(hi)); return r; }
; DEV void attn_item(LAS unsigned char* lds, const bf16_t* P, const bf16_t* QB, const bf16_t* KV, const bf16_t* KC, const bf16_t* VC, const float* rel_bias, bf16_t* OB, int b, int g, int qt) {
;     ...
;             const float inv = rs > 0.f ? 1.f / rs : 0.f;
; #pragma unroll
;             for (int kt = 0; kt < 8; ++kt) { sc[kt] = sc[kt] * inv; ia[kt] += (sc[kt][0] + sc[kt][1]) + (sc[kt][2] + sc[kt][3]); ib[kt] += sc[kt][3]; }
;             f32x4 Oc[4];
; #pragma unroll
;             for (int dt = 0; dt < 4; ++dt) Oc[dt] = (f32x4){0.f, 0.f, 0.f, 0.f};
; #pragma unroll
;             for (int kc = 0; kc < 4; ++kc) {
;                 if (2 * kc < nkt) {
;                     u32x4 w; w.x = cvt_pk_bf16(sc[2 * kc][0], sc[2 * kc][1]); w.y = cvt_pk_bf16(sc[2 * kc][2], sc[2 * kc][3]);
;                     w.z = cvt_pk_bf16(sc[2 * kc + 1][0], sc[2 * kc + 1][1]); w.w = cvt_pk_bf16(sc[2 * kc + 1][2], sc[2 * kc + 1][3]);
;                     const bf16x8 pf = as_bf16x8(w);
; #pragma unroll
;                     for (int dt = 0; dt < 4; ++dt) {
;                         const u32x2 va = *(const LAS u32x2*)(lds + vb2 + dt * 4352 + kc * 64);
;                         const u32x2 vb = *(const LAS u32x2*)(lds + vb2 + dt * 4352 + kc * 64 + 32);
;                         const bf16x8 vf = as_bf16x8((u32x4){va.x, va.y, vb.x, vb.y});
;                         Oc[dt] = __builtin_amdgcn_mfma_f32_16x16x32_bf16(vf, pf, Oc[dt], 0, 0, 0);
;                     }
;                 }
;             }
	v_add_f32_e32 v33, v33, v34
	ds_bpermute_b32 v34, v144, v33
	s_waitcnt lgkmcnt(0)
	v_add_f32_e32 v33, v33, v34
	v_div_scale_f32 v34, s[50:51], v33, v33, 1.0
	v_rcp_f32_e32 v35, v34
	s_nop 0
	v_fma_f32 v32, -v34, v35, 1.0
	v_fmac_f32_e32 v35, v32, v35
	v_div_scale_f32 v32, vcc, 1.0, v33, 1.0
	v_mul_f32_e32 v42, v32, v35
	v_fma_f32 v43, -v34, v42, v32
	v_fmac_f32_e32 v42, v43, v35
	v_fma_f32 v32, -v34, v42, v32
	v_div_fmas_f32 v32, v32, v35, v42
	v_div_fixup_f32 v32, v32, v33, 1.0
	v_cmp_lt_f32_e32 vcc, 0, v33
	s_nop 1
	v_cndmask_b32_e32 v58, 0, v32, vcc
	v_pk_mul_f32 v[60:61], v[4:5], v[58:59] op_sel_hi:[1,0]
	v_pk_mul_f32 v[64:65], v[2:3], v[58:59] op_sel_hi:[1,0]
	v_pk_mul_f32 v[62:63], v[40:41], v[58:59] op_sel_hi:[1,0]
	v_pk_mul_f32 v[66:67], v[38:39], v[58:59] op_sel_hi:[1,0]
	v_cvt_pk_bf16_f32 v40, v64, v65
	v_cvt_pk_bf16_f32 v41, v60, v61
	v_pk_mul_f32 v[74:75], v[36:37], v[58:59] op_sel_hi:[1,0]
	v_cvt_pk_bf16_f32 v42, v66, v67
	v_cvt_pk_bf16_f32 v43, v62, v63
	ds_read2_b64 v[2:5], v154 offset1:4
	ds_read2_b64 v[32:35], v155 offset0:32 offset1:36
	ds_read2_b64 v[80:83], v156 offset0:64 offset1:68
	ds_read2_b64 v[84:87], v157 offset0:96 offset1:100
	s_waitcnt lgkmcnt(3)
	v_mfma_f32_16x16x32_bf16 v[2:5], v[2:5], v[40:43], 0
	v_mul_f32_e64 v68, v70, v58
	v_mul_f32_e64 v69, v71, v58
	v_pk_mul_f32 v[70:71], v[76:77], v[58:59] op_sel_hi:[1,0]
	v_pk_mul_f32 v[72:73], v[72:73], v[58:59] op_sel_hi:[1,0]
	s_waitcnt lgkmcnt(2)
	v_mfma_f32_16x16x32_bf16 v[32:35], v[32:35], v[40:43], 0
	v_cndmask_b32_e64 v59, 0, 1, s[52:53]
	v_cmp_ne_u32_e64 s[50:51], 1, v59
	s_andn2_b64 vcc, exec, s[52:53]
	s_waitcnt lgkmcnt(1)
	v_mfma_f32_16x16x32_bf16 v[36:39], v[80:83], v[40:43], 0
	s_waitcnt lgkmcnt(0)
	v_mfma_f32_16x16x32_bf16 v[40:43], v[84:87], v[40:43], 0
	s_cbranch_vccnz .LBB0_187
	v_cvt_pk_bf16_f32 v80, v74, v75
	v_cvt_pk_bf16_f32 v81, v68, v69
	v_cvt_pk_bf16_f32 v82, v72, v73
	v_cvt_pk_bf16_f32 v83, v70, v71
	ds_read2_b64 v[84:87], v154 offset0:8 offset1:12
	ds_read2_b64 v[232:235], v155 offset0:40 offset1:44
	ds_read2_b64 v[236:239], v156 offset0:72 offset1:76
	ds_read2_b64 v[240:243], v157 offset0:104 offset1:108
	s_waitcnt lgkmcnt(3)
	v_mfma_f32_16x16x32_bf16 v[2:5], v[84:87], v[80:83], v[2:5]
	s_waitcnt lgkmcnt(2)
	v_mfma_f32_16x16x32_bf16 v[32:35], v[232:235], v[80:83], v[32:35]
	s_waitcnt lgkmcnt(1)
	v_mfma_f32_16x16x32_bf16 v[36:39], v[236:239], v[80:83], v[36:39]
	s_waitcnt lgkmcnt(0)
	v_mfma_f32_16x16x32_bf16 v[40:43], v[240:243], v[80:83], v[40:43]
.LBB0_187:
	v_mov_b32_e32 v59, v58
	v_mov_b32_e32 v86, v58
	v_mov_b32_e32 v87, v58
	v_pk_mul_f32 v[80:81], v[50:51], v[58:59]
	v_cndmask_b32_e64 v50, 0, 1, s[54:55]
	v_pk_mul_f32 v[76:77], v[54:55], v[86:87]
	v_pk_mul_f32 v[78:79], v[78:79], v[86:87]
	v_cmp_ne_u32_e64 s[52:53], 1, v50
	s_andn2_b64 vcc, exec, s[54:55]
	v_pk_mul_f32 v[82:83], v[56:57], v[58:59]
	s_cbranch_vccnz .LBB0_189
	v_cvt_pk_bf16_f32 v54, v80, v81
	v_cvt_pk_bf16_f32 v55, v76, v77
	v_cvt_pk_bf16_f32 v56, v82, v83
	v_cvt_pk_bf16_f32 v57, v78, v79
	ds_read2_b64 v[88:91], v154 offset0:16 offset1:20
	ds_read2_b64 v[232:235], v155 offset0:48 offset1:52
	ds_read2_b64 v[236:239], v156 offset0:80 offset1:84
	ds_read2_b64 v[240:243], v157 offset0:112 offset1:116
	s_waitcnt lgkmcnt(3)
	v_mfma_f32_16x16x32_bf16 v[2:5], v[88:91], v[54:57], v[2:5]
	s_waitcnt lgkmcnt(2)
	v_mfma_f32_16x16x32_bf16 v[32:35], v[232:235], v[54:57], v[32:35]
	s_waitcnt lgkmcnt(1)
	v_mfma_f32_16x16x32_bf16 v[36:39], v[236:239], v[54:57], v[36:39]
	s_waitcnt lgkmcnt(0)
	v_mfma_f32_16x16x32_bf16 v[40:43], v[240:243], v[54:57], v[40:43]
.LBB0_189:
	v_pk_mul_f32 v[88:89], v[44:45], v[58:59]
	v_cndmask_b32_e64 v44, 0, 1, s[6:7]
	v_pk_mul_f32 v[84:85], v[46:47], v[86:87]
	v_pk_mul_f32 v[86:87], v[52:53], v[86:87]
	v_cmp_ne_u32_e64 s[54:55], 1, v44
	s_andn2_b64 vcc, exec, s[6:7]
	v_pk_mul_f32 v[90:91], v[48:49], v[58:59]
	s_cbranch_vccnz .LBB0_191
	v_cvt_pk_bf16_f32 v44, v88, v89
	v_cvt_pk_bf16_f32 v45, v84, v85
	v_cvt_pk_bf16_f32 v46, v90, v91
	v_cvt_pk_bf16_f32 v47, v86, v87
	ds_read2_b64 v[48:51], v154 offset0:24 offset1:28
	ds_read2_b64 v[232:235], v155 offset0:56 offset1:60
	ds_read2_b64 v[236:239], v156 offset0:88 offset1:92
	ds_read2_b64 v[240:243], v157 offset0:120 offset1:124
	s_waitcnt lgkmcnt(3)
	v_mfma_f32_16x16x32_bf16 v[2:5], v[48:51], v[44:47], v[2:5]
	s_waitcnt lgkmcnt(2)
	v_mfma_f32_16x16x32_bf16 v[32:35], v[232:235], v[44:47], v[32:35]
	s_waitcnt lgkmcnt(1)
	v_mfma_f32_16x16x32_bf16 v[36:39], v[236:239], v[44:47], v[36:39]
	s_waitcnt lgkmcnt(0)
	v_mfma_f32_16x16x32_bf16 v[40:43], v[240:243], v[44:47], v[40:43]

; #define LAS __attribute__((address_space(3)))
; DEV void attn_item(LAS unsigned char* lds, const bf16_t* P, const bf16_t* QB, const bf16_t* KV, const bf16_t* KC, const bf16_t* VC, const float* rel_bias, bf16_t* OB, int b, int g, int qt) {
;     ...
;                     for (int r = 0; r < 4; ++r) { const int n = kt * 16 + g4 * 4 + r; const int dist = tl - (16 * n + 31);
;                         const int idx = dist < 0 ? 0 : (dist > 128 ? 128 : dist);
;                         const float s = a[r] + *(const LAS float*)(lds + btb + idx * 4 + hh * 516);
;                         a[r] = dist >= 0 ? s : NEG_; }
;                     sc[kt] = a;
;                 } else sc[kt] = (f32x4){NEG_, NEG_, NEG_, NEG_};
;             }
;             float mx = NEG_;
; #pragma unroll
;             for (int kt = 0; kt < 8; ++kt)
; #pragma unroll
;                 for (int r = 0; r < 4; ++r) mx = fmaxf(mx, sc[kt][r]);
;             mx = fmaxf(mx, __shfl_xor(mx, 16)); mx = fmaxf(mx, __shfl_xor(mx, 32));
;             float rs = 0.f;
; #pragma unroll
;             for (int kt = 0; kt < 8; ++kt)
; #pragma unroll
;                 for (int r = 0; r < 4; ++r) { const float s = sc[kt][r]; const float p = s > -1e29f ? __builtin_amdgcn_exp2f(s - mx) : 0.f; sc[kt][r] = p; rs += p; }
;             rs += __shfl_xor(rs, 16); rs += __shfl_xor(rs, 32);
.LBB0_205:
	s_waitcnt lgkmcnt(3)
	v_add_f32_e32 v44, v44, v56
	s_waitcnt lgkmcnt(2)
	v_add_f32_e32 v45, v45, v55
	v_cndmask_b32_e64 v44, v223, v44, s[42:43]
	v_cndmask_b32_e64 v45, v223, v45, s[44:45]
	s_waitcnt lgkmcnt(1)
	v_add_f32_e32 v46, v46, v54
	s_waitcnt lgkmcnt(0)
	v_add_f32_e32 v47, v47, v53
	s_mov_b32 s4, 0xf149f2ca
	v_cndmask_b32_e64 v46, v223, v46, s[46:47]
	v_cndmask_b32_e64 v47, v223, v47, s[48:49]
	v_max3_f32 v53, v44, s4, v45
	v_max3_f32 v53, v53, v46, v47
	v_max3_f32 v53, v53, v51, v52
	v_max3_f32 v53, v53, v49, v50
	v_max3_f32 v53, v53, v48, v59
	v_max3_f32 v53, v53, v57, v58
	v_max3_f32 v53, v53, v95, v102
	v_max3_f32 v53, v53, v93, v94
	v_max3_f32 v53, v53, v92, v105
	v_max3_f32 v53, v53, v103, v104
	v_max3_f32 v53, v53, v109, v110
	v_max3_f32 v53, v53, v107, v108
	v_max3_f32 v53, v53, v106, v113
	v_max3_f32 v53, v53, v111, v112
	v_max3_f32 v53, v53, v114, v119
	v_max3_f32 v53, v53, v115, v123
	ds_bpermute_b32 v54, v143, v53
	v_cmp_lt_f32_e32 vcc, s65, v44
	s_waitcnt lgkmcnt(0)
	v_max_f32_e32 v54, v54, v54
	v_max_f32_e32 v53, v53, v54
	ds_bpermute_b32 v54, v144, v53
	s_waitcnt lgkmcnt(0)
	v_max_f32_e32 v54, v54, v54
	v_max_f32_e32 v56, v53, v54
	v_sub_f32_e32 v53, v44, v56
	v_exp_f32_e32 v53, v53
	v_sub_f32_e32 v54, v45, v56
	v_exp_f32_e32 v54, v54
	v_sub_f32_e32 v55, v47, v56
	v_cndmask_b32_e32 v44, 0, v53, vcc
	v_cmp_lt_f32_e32 vcc, s65, v45
	v_exp_f32_e32 v55, v55
	v_add_f32_e32 v53, 0, v44
	v_cndmask_b32_e32 v45, 0, v54, vcc
	v_sub_f32_e32 v54, v46, v56
	v_exp_f32_e32 v54, v54
	v_cmp_lt_f32_e32 vcc, s65, v46
	v_add_f32_e32 v53, v45, v53
	s_nop 0
	v_cndmask_b32_e32 v46, 0, v54, vcc
	v_sub_f32_e32 v54, v51, v56
	v_exp_f32_e32 v54, v54
	v_cmp_lt_f32_e32 vcc, s65, v47
	v_add_f32_e32 v53, v46, v53
	s_nop 0
	v_cndmask_b32_e32 v47, 0, v55, vcc
	v_sub_f32_e32 v55, v52, v56
	v_cmp_lt_f32_e32 vcc, s65, v51
	v_exp_f32_e32 v55, v55
	v_add_f32_e32 v53, v47, v53
	v_cndmask_b32_e32 v54, 0, v54, vcc
	v_cmp_lt_f32_e32 vcc, s65, v52
	v_sub_f32_e32 v52, v49, v56
	v_exp_f32_e32 v52, v52
	v_add_f32_e32 v51, v54, v53
	v_cndmask_b32_e32 v55, 0, v55, vcc
	v_sub_f32_e32 v53, v50, v56
	v_cmp_lt_f32_e32 vcc, s65, v49
	v_exp_f32_e32 v53, v53
	v_add_f32_e32 v51, v55, v51
	v_cndmask_b32_e32 v52, 0, v52, vcc
	v_cmp_lt_f32_e32 vcc, s65, v50
	v_sub_f32_e32 v50, v48, v56
	v_exp_f32_e32 v50, v50
	v_add_f32_e32 v49, v52, v51
	v_cndmask_b32_e32 v53, 0, v53, vcc
	v_cmp_lt_f32_e32 vcc, s65, v48
	v_add_f32_e32 v49, v53, v49
	v_sub_f32_e32 v51, v59, v56
	v_cndmask_b32_e32 v158, 0, v50, vcc
	v_exp_f32_e32 v51, v51
	v_add_f32_e32 v48, v158, v49
	v_sub_f32_e32 v49, v57, v56
	v_exp_f32_e32 v49, v49
	v_sub_f32_e32 v50, v58, v56
	v_exp_f32_e32 v50, v50
	v_cmp_lt_f32_e32 vcc, s65, v59
	s_nop 1
	v_cndmask_b32_e32 v159, 0, v51, vcc
	v_cmp_lt_f32_e32 vcc, s65, v57
	v_add_f32_e32 v48, v159, v48
	s_nop 0
	v_cndmask_b32_e32 v160, 0, v49, vcc
	v_cmp_lt_f32_e32 vcc, s65, v58
	v_sub_f32_e32 v49, v95, v56
	v_exp_f32_e32 v49, v49
	v_cndmask_b32_e32 v161, 0, v50, vcc
	v_sub_f32_e32 v50, v102, v56
	v_exp_f32_e32 v50, v50
	v_cmp_lt_f32_e32 vcc, s65, v95
	v_add_f32_e32 v48, v160, v48
	v_add_f32_e32 v48, v161, v48
	v_cndmask_b32_e32 v162, 0, v49, vcc
	v_cmp_lt_f32_e32 vcc, s65, v102
	v_sub_f32_e32 v49, v93, v56
	v_exp_f32_e32 v49, v49
	v_cndmask_b32_e32 v163, 0, v50, vcc
	v_sub_f32_e32 v50, v94, v56
	v_exp_f32_e32 v50, v50
	v_cmp_lt_f32_e32 vcc, s65, v93
	v_add_f32_e32 v48, v162, v48
	v_add_f32_e32 v48, v163, v48
	v_cndmask_b32_e32 v164, 0, v49, vcc
	v_cmp_lt_f32_e32 vcc, s65, v94
	v_sub_f32_e32 v49, v92, v56
	v_exp_f32_e32 v49, v49
	v_cndmask_b32_e32 v165, 0, v50, vcc
	v_sub_f32_e32 v50, v105, v56
	v_exp_f32_e32 v50, v50
	v_cmp_lt_f32_e32 vcc, s65, v92
	v_add_f32_e32 v48, v164, v48
	v_add_f32_e32 v48, v165, v48
	v_cndmask_b32_e32 v120, 0, v49, vcc
	v_cmp_lt_f32_e32 vcc, s65, v105
	v_sub_f32_e32 v49, v103, v56
	v_exp_f32_e32 v49, v49
	v_cndmask_b32_e32 v121, 0, v50, vcc
	v_sub_f32_e32 v50, v104, v56
	v_exp_f32_e32 v50, v50
	v_cmp_lt_f32_e32 vcc, s65, v103
	v_add_f32_e32 v48, v120, v48
	v_add_f32_e32 v48, v121, v48
	v_cndmask_b32_e32 v124, 0, v49, vcc
	v_cmp_lt_f32_e32 vcc, s65, v104
	v_sub_f32_e32 v49, v109, v56
	v_exp_f32_e32 v49, v49
	v_cndmask_b32_e32 v125, 0, v50, vcc
	v_sub_f32_e32 v50, v110, v56
	v_exp_f32_e32 v50, v50
	v_cmp_lt_f32_e32 vcc, s65, v109
	v_add_f32_e32 v48, v124, v48
	v_add_f32_e32 v48, v125, v48
	v_cndmask_b32_e32 v126, 0, v49, vcc
	v_cmp_lt_f32_e32 vcc, s65, v110
	v_sub_f32_e32 v49, v107, v56
	v_exp_f32_e32 v49, v49
	v_cndmask_b32_e32 v127, 0, v50, vcc
	v_sub_f32_e32 v50, v108, v56
	v_exp_f32_e32 v50, v50
	v_cmp_lt_f32_e32 vcc, s65, v107
	v_add_f32_e32 v48, v126, v48
	v_add_f32_e32 v48, v127, v48
	v_cndmask_b32_e32 v130, 0, v49, vcc
	v_cmp_lt_f32_e32 vcc, s65, v108
	v_sub_f32_e32 v49, v106, v56
	v_exp_f32_e32 v49, v49
	v_cndmask_b32_e32 v131, 0, v50, vcc
	v_sub_f32_e32 v50, v113, v56
	v_exp_f32_e32 v50, v50
	v_cmp_lt_f32_e32 vcc, s65, v106
	v_add_f32_e32 v48, v130, v48
	v_add_f32_e32 v48, v131, v48
	v_cndmask_b32_e32 v106, 0, v49, vcc
	v_cmp_lt_f32_e32 vcc, s65, v113
	v_sub_f32_e32 v49, v111, v56
	v_exp_f32_e32 v49, v49
	v_cndmask_b32_e32 v107, 0, v50, vcc
	v_sub_f32_e32 v50, v112, v56
	v_exp_f32_e32 v50, v50
	v_cmp_lt_f32_e32 vcc, s65, v111
	v_add_f32_e32 v48, v106, v48
	v_add_f32_e32 v48, v107, v48
	v_cndmask_b32_e32 v116, 0, v49, vcc
	v_cmp_lt_f32_e32 vcc, s65, v112
	v_sub_f32_e32 v49, v114, v56
	v_exp_f32_e32 v49, v49
	v_cndmask_b32_e32 v117, 0, v50, vcc
	v_sub_f32_e32 v50, v119, v56
	v_exp_f32_e32 v50, v50
	v_cmp_lt_f32_e32 vcc, s65, v114
	v_add_f32_e32 v48, v116, v48
	v_add_f32_e32 v48, v117, v48
	v_cndmask_b32_e32 v118, 0, v49, vcc
	v_cmp_lt_f32_e32 vcc, s65, v119
	v_sub_f32_e32 v49, v115, v56
	v_exp_f32_e32 v49, v49
	v_cndmask_b32_e32 v119, 0, v50, vcc
	v_sub_f32_e32 v50, v123, v56
	v_exp_f32_e32 v50, v50
	v_add_f32_e32 v48, v118, v48
	v_cmp_lt_f32_e32 vcc, s65, v115
	v_add_f32_e32 v48, v119, v48
	s_nop 0
	v_cndmask_b32_e32 v122, 0, v49, vcc
	v_cmp_lt_f32_e32 vcc, s65, v123
	v_add_f32_e32 v48, v122, v48
	s_nop 0
	v_cndmask_b32_e32 v123, 0, v50, vcc
	v_add_f32_e32 v48, v123, v48
	ds_bpermute_b32 v49, v143, v48
	s_waitcnt lgkmcnt(0)
; #define LAS __attribute__((address_space(3)))
; DEV unsigned cvt_pk_bf16(float lo, float hi) { unsigned r; asm volatile("v_cvt_pk_bf16_f32 %0, %1, %2" : "=v"(r) : "v"(lo), "v"(hi)); return r; }
; DEV void attn_item(LAS unsigned char* lds, const bf16_t* P, const bf16_t* QB, const bf16_t* KV, const bf16_t* KC, const bf16_t* VC, const float* rel_bias, bf16_t* OB, int b, int g, int qt) {
;     ...
;             const float inv = rs > 0.f ? 1.f / rs : 0.f;
; #pragma unroll
;             for (int kt = 0; kt < 8; ++kt) { sc[kt] = sc[kt] * inv; ia[kt] += (sc[kt][0] + sc[kt][1]) + (sc[kt][2] + sc[kt][3]); ib[kt] += sc[kt][3]; }
;             f32x4 Oc[4];
; #pragma unroll
;             for (int dt = 0; dt < 4; ++dt) Oc[dt] = (f32x4){0.f, 0.f, 0.f, 0.f};
; #pragma unroll
;             for (int kc = 0; kc < 4; ++kc) {
;                 if (2 * kc < nkt) {
;                     u32x4 w; w.x = cvt_pk_bf16(sc[2 * kc][0], sc[2 * kc][1]); w.y = cvt_pk_bf16(sc[2 * kc][2], sc[2 * kc][3]);
;                     w.z = cvt_pk_bf16(sc[2 * kc + 1][0], sc[2 * kc + 1][1]); w.w = cvt_pk_bf16(sc[2 * kc + 1][2], sc[2 * kc + 1][3]);
;                     const bf16x8 pf = as_bf16x8(w);
; #pragma unroll
;                     for (int dt = 0; dt < 4; ++dt) {
;                         const u32x2 va = *(const LAS u32x2*)(lds + vb2 + dt * 4352 + kc * 64);
;                         const u32x2 vb = *(const LAS u32x2*)(lds + vb2 + dt * 4352 + kc * 64 + 32);
;                         const bf16x8 vf = as_bf16x8((u32x4){va.x, va.y, vb.x, vb.y});
;                         Oc[dt] = __builtin_amdgcn_mfma_f32_16x16x32_bf16(vf, pf, Oc[dt], 0, 0, 0);
;                     }
;                 }
;             }
	v_add_f32_e32 v48, v48, v49
	ds_bpermute_b32 v49, v144, v48
	s_waitcnt lgkmcnt(0)
	v_add_f32_e32 v48, v48, v49
	v_div_scale_f32 v49, s[4:5], v48, v48, 1.0
	v_rcp_f32_e32 v50, v49
	s_nop 0
	v_fma_f32 v51, -v49, v50, 1.0
	v_fmac_f32_e32 v50, v51, v50
	v_div_scale_f32 v51, vcc, 1.0, v48, 1.0
	v_mul_f32_e32 v56, v51, v50
	v_fma_f32 v57, -v49, v56, v51
	v_fmac_f32_e32 v56, v57, v50
	v_fma_f32 v49, -v49, v56, v51
	v_div_fmas_f32 v49, v49, v50, v56
	v_div_fixup_f32 v49, v49, v48, 1.0
	v_cmp_lt_f32_e32 vcc, 0, v48
	s_nop 1
	v_cndmask_b32_e32 v128, 0, v49, vcc
	v_pk_mul_f32 v[92:93], v[46:47], v[128:129] op_sel_hi:[1,0]
	v_pk_mul_f32 v[102:103], v[44:45], v[128:129] op_sel_hi:[1,0]
	v_pk_mul_f32 v[94:95], v[52:53], v[128:129] op_sel_hi:[1,0]
	v_pk_mul_f32 v[104:105], v[54:55], v[128:129] op_sel_hi:[1,0]
	v_cvt_pk_bf16_f32 v56, v102, v103
	v_cvt_pk_bf16_f32 v57, v92, v93
	v_pk_mul_f32 v[110:111], v[160:161], v[128:129] op_sel_hi:[1,0]
	v_cvt_pk_bf16_f32 v58, v104, v105
	v_cvt_pk_bf16_f32 v59, v94, v95
	ds_read2_b64 v[44:47], v154 offset1:4
	ds_read2_b64 v[48:51], v155 offset0:32 offset1:36
	ds_read2_b64 v[52:55], v156 offset0:64 offset1:68
	ds_read2_b64 v[132:135], v157 offset0:96 offset1:100
	s_waitcnt lgkmcnt(3)
	v_mfma_f32_16x16x32_bf16 v[44:47], v[44:47], v[56:59], 0
	v_mul_f32_e64 v114, v158, v128
	v_mul_f32_e64 v115, v159, v128
	v_pk_mul_f32 v[108:109], v[164:165], v[128:129] op_sel_hi:[1,0]
	v_pk_mul_f32 v[112:113], v[162:163], v[128:129] op_sel_hi:[1,0]
	s_waitcnt lgkmcnt(2)
	v_mfma_f32_16x16x32_bf16 v[48:51], v[48:51], v[56:59], 0
	s_and_b64 vcc, exec, s[50:51]
	s_waitcnt lgkmcnt(1)
	v_mfma_f32_16x16x32_bf16 v[52:55], v[52:55], v[56:59], 0
	s_waitcnt lgkmcnt(0)
	v_mfma_f32_16x16x32_bf16 v[56:59], v[132:135], v[56:59], 0
	s_cbranch_vccnz .LBB0_207
	v_cvt_pk_bf16_f32 v132, v114, v115
	v_cvt_pk_bf16_f32 v133, v110, v111
	v_cvt_pk_bf16_f32 v134, v112, v113
	v_cvt_pk_bf16_f32 v135, v108, v109
	ds_read2_b64 v[158:161], v154 offset0:8 offset1:12
	ds_read2_b64 v[232:235], v155 offset0:40 offset1:44
	ds_read2_b64 v[236:239], v156 offset0:72 offset1:76
	ds_read2_b64 v[240:243], v157 offset0:104 offset1:108
	s_waitcnt lgkmcnt(3)
	v_mfma_f32_16x16x32_bf16 v[44:47], v[158:161], v[132:135], v[44:47]
	s_waitcnt lgkmcnt(2)
	v_mfma_f32_16x16x32_bf16 v[48:51], v[232:235], v[132:135], v[48:51]
	s_waitcnt lgkmcnt(1)
	v_mfma_f32_16x16x32_bf16 v[52:55], v[236:239], v[132:135], v[52:55]
	s_waitcnt lgkmcnt(0)
	v_mfma_f32_16x16x32_bf16 v[56:59], v[240:243], v[132:135], v[56:59]
.LBB0_207:
	v_mov_b32_e32 v129, v128
	v_mov_b32_e32 v134, v128
	v_mov_b32_e32 v135, v128
	v_pk_mul_f32 v[124:125], v[124:125], v[134:135]
	v_pk_mul_f32 v[132:133], v[120:121], v[128:129]
	v_pk_mul_f32 v[120:121], v[130:131], v[134:135]
	s_and_b64 vcc, exec, s[52:53]
	v_pk_mul_f32 v[126:127], v[126:127], v[128:129]
	s_cbranch_vccnz .LBB0_209
	v_cvt_pk_bf16_f32 v158, v132, v133
	v_cvt_pk_bf16_f32 v159, v124, v125
	v_cvt_pk_bf16_f32 v160, v126, v127
	v_cvt_pk_bf16_f32 v161, v120, v121
	ds_read2_b64 v[162:165], v154 offset0:16 offset1:20
	ds_read2_b64 v[232:235], v155 offset0:48 offset1:52
	ds_read2_b64 v[236:239], v156 offset0:80 offset1:84
	ds_read2_b64 v[240:243], v157 offset0:112 offset1:116
	s_waitcnt lgkmcnt(3)
	v_mfma_f32_16x16x32_bf16 v[44:47], v[162:165], v[158:161], v[44:47]
	s_waitcnt lgkmcnt(2)
	v_mfma_f32_16x16x32_bf16 v[48:51], v[232:235], v[158:161], v[48:51]
	s_waitcnt lgkmcnt(1)
	v_mfma_f32_16x16x32_bf16 v[52:55], v[236:239], v[158:161], v[52:55]
	s_waitcnt lgkmcnt(0)
	v_mfma_f32_16x16x32_bf16 v[56:59], v[240:243], v[158:161], v[56:59]
